# v47 + up-proj output U stored with the default cache policy instead of nt
# speedup vs baseline: 1.0116x; 1.0116x over previous
; __device__ __forceinline__ unsigned cvt_pk_bf16(float lo, float hi) { unsigned r; asm volatile("v_cvt_pk_bf16_f32 %0, %1, %2" : "=v"(r) : "v"(lo), "v"(hi)); return r; }
;     DI void operator()(const f32x4 (&acc)[2][2][4][2], const Unit& u, int wr, int wc, int fr, int fq) const {
;     ...
;             for (int m = 0; m < 4; ++m) { const int row = row0 + ai * 128 + m * 16; const float s = rsqrtf(ssum2[row] * (1.f / 1024.f) + EPS);
;                 bf16_t* rowp = U + (size_t)row * 4096 + col0;
; #pragma unroll
;                 for (int bj = 0; bj < 2; ++bj) { f32x4 v0 = acc[ai][bj][m][0] * s, v1 = acc[ai][bj][m][1] * s;
; #pragma unroll
;                     for (int j = 0; j < 4; ++j) { const float a = fmaxf(v0[j], 0.f), b = fmaxf(v1[j], 0.f); v0[j] = a * a; v1[j] = b * b; }
;                     u32x4 w; w.x = cvt_pk_bf16(v0[0], v0[1]); w.y = cvt_pk_bf16(v0[2], v0[3]); w.z = cvt_pk_bf16(v1[0], v1[1]); w.w = cvt_pk_bf16(v1[2], v1[3]);
;                     __builtin_nontemporal_store(w, (u32x4*)(rowp + bj * 128)); } }
.LBB0_2070:
	v_lshl_add_u32 v148, s6, 8, v152
	v_ashrrev_i32_e32 v149, 31, v148
	v_lshl_add_u64 v[144:145], v[148:149], 2, s[16:17]
	global_load_dword v159, v[144:145], off
	global_load_dword v226, v[144:145], off offset:64
	global_load_dword v227, v[144:145], off offset:128
	global_load_dword v228, v[144:145], off offset:192
	global_load_dword v229, v[144:145], off offset:512
	global_load_dword v230, v[144:145], off offset:576
	global_load_dword v231, v[144:145], off offset:640
	global_load_dword v232, v[144:145], off offset:704
	v_lshl_or_b32 v146, s7, 8, v154
	v_ashrrev_i32_e32 v147, 31, v146
	v_lshlrev_b64 v[150:151], 1, v[146:147]
	v_lshlrev_b64 v[162:163], 13, v[148:149]
	v_or_b32_e32 v160, 16, v148
	v_ashrrev_i32_e32 v161, 31, v160
	s_waitcnt vmcnt(0)
	v_fmamk_f32 v146, v159, 0x3a800000, v158
	v_mul_f32_e32 v147, 0x4b800000, v146
	v_cmp_gt_f32_e32 vcc, s62, v146
	s_nop 1
	v_cndmask_b32_e32 v146, v146, v147, vcc
	v_rsq_f32_e32 v149, v146
	v_lshl_add_u64 v[146:147], s[14:15], 0, v[162:163]
	v_lshl_add_u64 v[146:147], v[146:147], 0, v[150:151]
	v_lshl_add_u64 v[162:163], v[160:161], 2, s[16:17]
	v_mul_f32_e32 v159, 0x45800000, v149
	v_cndmask_b32_e32 v164, v149, v159, vcc
	v_mul_f32_e32 v126, v126, v164
	v_mul_f32_e32 v127, v127, v164
	v_mul_f32_e32 v124, v124, v164
	v_mul_f32_e32 v125, v125, v164
	v_mul_f32_e32 v122, v122, v164
	v_mul_f32_e32 v123, v123, v164
	v_mul_f32_e32 v120, v120, v164
	v_mul_f32_e32 v121, v121, v164
	v_mul_f32_e32 v114, v114, v164
	v_mul_f32_e32 v115, v115, v164
	v_mul_f32_e32 v112, v112, v164
	v_mul_f32_e32 v113, v113, v164
	v_mul_f32_e32 v118, v118, v164
	v_mul_f32_e32 v119, v119, v164
	v_mul_f32_e32 v116, v116, v164
	v_mul_f32_e32 v117, v117, v164
	v_max_f32_e32 v124, 0, v124
	v_max_f32_e32 v120, 0, v120
	v_max_f32_e32 v125, 0, v125
	v_max_f32_e32 v121, 0, v121
	v_max_f32_e32 v126, 0, v126
	v_max_f32_e32 v122, 0, v122
	v_max_f32_e32 v127, 0, v127
	v_max_f32_e32 v123, 0, v123
	v_max_f32_e32 v112, 0, v112
	v_max_f32_e32 v113, 0, v113
	v_max_f32_e32 v114, 0, v114
	v_max_f32_e32 v115, 0, v115
	v_max_f32_e32 v116, 0, v116
	v_max_f32_e32 v117, 0, v117
	v_max_f32_e32 v118, 0, v118
	v_max_f32_e32 v119, 0, v119
	v_mul_f32_e32 v124, v124, v124
	v_mul_f32_e32 v120, v120, v120
	v_mul_f32_e32 v125, v125, v125
	v_mul_f32_e32 v121, v121, v121
	v_mul_f32_e32 v126, v126, v126
	v_mul_f32_e32 v122, v122, v122
	v_mul_f32_e32 v127, v127, v127
	v_mul_f32_e32 v123, v123, v123
	v_mul_f32_e32 v149, v112, v112
	v_mul_f32_e32 v159, v113, v113
	v_mul_f32_e32 v164, v114, v114
	v_mul_f32_e32 v165, v115, v115
	v_cvt_pk_bf16_f32 v112, v124, v125
	v_cvt_pk_bf16_f32 v113, v126, v127
	v_cvt_pk_bf16_f32 v114, v120, v121
	v_cvt_pk_bf16_f32 v115, v122, v123
	v_mul_f32_e32 v116, v116, v116
	v_mul_f32_e32 v117, v117, v117
	v_mul_f32_e32 v118, v118, v118
	v_mul_f32_e32 v119, v119, v119
	global_store_dwordx4 v[146:147], v[112:115], off
	s_nop 1
	v_cvt_pk_bf16_f32 v112, v116, v117
	v_cvt_pk_bf16_f32 v113, v118, v119
	v_cvt_pk_bf16_f32 v114, v149, v159
	v_cvt_pk_bf16_f32 v115, v164, v165
	global_store_dwordx4 v[146:147], v[112:115], off offset:256
	s_nop 0
	s_nop 0
	v_fmamk_f32 v116, v226, 0x3a800000, v158
	v_mul_f32_e32 v117, 0x4b800000, v116
	v_cmp_gt_f32_e32 vcc, s62, v116
	v_lshlrev_b64 v[114:115], 13, v[160:161]
	v_or_b32_e32 v112, 32, v148
	v_cndmask_b32_e32 v116, v116, v117, vcc
	v_rsq_f32_e32 v118, v116
	v_lshl_add_u64 v[114:115], s[14:15], 0, v[114:115]
	v_ashrrev_i32_e32 v113, 31, v112
	v_lshl_add_u64 v[114:115], v[114:115], 0, v[150:151]
	v_mul_f32_e32 v119, 0x45800000, v118
	v_cndmask_b32_e32 v118, v118, v119, vcc
	v_mul_f32_e32 v110, v110, v118
	v_mul_f32_e32 v111, v111, v118
	v_mul_f32_e32 v108, v108, v118
	v_mul_f32_e32 v109, v109, v118
	v_mul_f32_e32 v106, v106, v118
	v_mul_f32_e32 v107, v107, v118
	v_mul_f32_e32 v104, v104, v118
	v_mul_f32_e32 v105, v105, v118
	v_mul_f32_e32 v98, v98, v118
	v_mul_f32_e32 v99, v99, v118
	v_mul_f32_e32 v96, v96, v118
	v_mul_f32_e32 v97, v97, v118
	v_mul_f32_e32 v102, v102, v118
	v_mul_f32_e32 v103, v103, v118
	v_mul_f32_e32 v100, v100, v118
	v_mul_f32_e32 v101, v101, v118
	v_max_f32_e32 v108, 0, v108
	v_max_f32_e32 v104, 0, v104
	v_max_f32_e32 v109, 0, v109
	v_max_f32_e32 v105, 0, v105
	v_max_f32_e32 v110, 0, v110
	v_max_f32_e32 v106, 0, v106
	v_max_f32_e32 v111, 0, v111
	v_max_f32_e32 v107, 0, v107
	v_max_f32_e32 v96, 0, v96
	v_max_f32_e32 v97, 0, v97
	v_max_f32_e32 v98, 0, v98
	v_max_f32_e32 v99, 0, v99
	v_max_f32_e32 v100, 0, v100
	v_max_f32_e32 v101, 0, v101
	v_max_f32_e32 v102, 0, v102
	v_max_f32_e32 v103, 0, v103
	v_mul_f32_e32 v108, v108, v108
	v_mul_f32_e32 v104, v104, v104
	v_mul_f32_e32 v109, v109, v109
	v_mul_f32_e32 v105, v105, v105
	v_mul_f32_e32 v110, v110, v110
	v_mul_f32_e32 v106, v106, v106
	v_mul_f32_e32 v111, v111, v111
	v_mul_f32_e32 v107, v107, v107
	v_mul_f32_e32 v118, v96, v96
	v_mul_f32_e32 v119, v97, v97
	v_mul_f32_e32 v120, v98, v98
	v_mul_f32_e32 v121, v99, v99
	v_cvt_pk_bf16_f32 v96, v108, v109
	v_cvt_pk_bf16_f32 v97, v110, v111
	v_cvt_pk_bf16_f32 v98, v104, v105
	v_cvt_pk_bf16_f32 v99, v106, v107
	v_lshl_add_u64 v[116:117], v[112:113], 2, s[16:17]
	v_mul_f32_e32 v100, v100, v100
	v_mul_f32_e32 v101, v101, v101
	v_mul_f32_e32 v102, v102, v102
	v_mul_f32_e32 v103, v103, v103
	global_store_dwordx4 v[114:115], v[96:99], off
	s_nop 1
	v_cvt_pk_bf16_f32 v96, v100, v101
	v_cvt_pk_bf16_f32 v97, v102, v103
	v_cvt_pk_bf16_f32 v98, v118, v119
	v_cvt_pk_bf16_f32 v99, v120, v121
	global_store_dwordx4 v[114:115], v[96:99], off offset:256
	s_nop 0
	s_nop 0
	v_fmamk_f32 v100, v227, 0x3a800000, v158
	v_mul_f32_e32 v101, 0x4b800000, v100
	v_cmp_gt_f32_e32 vcc, s62, v100
; __device__ __forceinline__ unsigned cvt_pk_bf16(float lo, float hi) { unsigned r; asm volatile("v_cvt_pk_bf16_f32 %0, %1, %2" : "=v"(r) : "v"(lo), "v"(hi)); return r; }
;     DI void operator()(const f32x4 (&acc)[2][2][4][2], const Unit& u, int wr, int wc, int fr, int fq) const {
;     ...
;             for (int m = 0; m < 4; ++m) { const int row = row0 + ai * 128 + m * 16; const float s = rsqrtf(ssum2[row] * (1.f / 1024.f) + EPS);
;                 bf16_t* rowp = U + (size_t)row * 4096 + col0;
; #pragma unroll
;                 for (int bj = 0; bj < 2; ++bj) { f32x4 v0 = acc[ai][bj][m][0] * s, v1 = acc[ai][bj][m][1] * s;
; #pragma unroll
;                     for (int j = 0; j < 4; ++j) { const float a = fmaxf(v0[j], 0.f), b = fmaxf(v1[j], 0.f); v0[j] = a * a; v1[j] = b * b; }
;                     u32x4 w; w.x = cvt_pk_bf16(v0[0], v0[1]); w.y = cvt_pk_bf16(v0[2], v0[3]); w.z = cvt_pk_bf16(v1[0], v1[1]); w.w = cvt_pk_bf16(v1[2], v1[3]);
;                     __builtin_nontemporal_store(w, (u32x4*)(rowp + bj * 128)); } }
	v_lshlrev_b64 v[98:99], 13, v[112:113]
	v_or_b32_e32 v96, 48, v148
	v_cndmask_b32_e32 v100, v100, v101, vcc
	v_rsq_f32_e32 v102, v100
	v_lshl_add_u64 v[98:99], s[14:15], 0, v[98:99]
	v_ashrrev_i32_e32 v97, 31, v96
	v_lshl_add_u64 v[98:99], v[98:99], 0, v[150:151]
	v_mul_f32_e32 v103, 0x45800000, v102
	v_cndmask_b32_e32 v102, v102, v103, vcc
	v_mul_f32_e32 v94, v94, v102
	v_mul_f32_e32 v95, v95, v102
	v_mul_f32_e32 v92, v92, v102
	v_mul_f32_e32 v93, v93, v102
	v_mul_f32_e32 v90, v90, v102
	v_mul_f32_e32 v91, v91, v102
	v_mul_f32_e32 v88, v88, v102
	v_mul_f32_e32 v89, v89, v102
	v_mul_f32_e32 v82, v82, v102
	v_mul_f32_e32 v83, v83, v102
	v_mul_f32_e32 v80, v80, v102
	v_mul_f32_e32 v81, v81, v102
	v_mul_f32_e32 v86, v86, v102
	v_mul_f32_e32 v87, v87, v102
	v_mul_f32_e32 v84, v84, v102
	v_mul_f32_e32 v85, v85, v102
	v_max_f32_e32 v92, 0, v92
	v_max_f32_e32 v88, 0, v88
	v_max_f32_e32 v93, 0, v93
	v_max_f32_e32 v89, 0, v89
	v_max_f32_e32 v94, 0, v94
	v_max_f32_e32 v90, 0, v90
	v_max_f32_e32 v95, 0, v95
	v_max_f32_e32 v91, 0, v91
	v_max_f32_e32 v80, 0, v80
	v_max_f32_e32 v81, 0, v81
	v_max_f32_e32 v82, 0, v82
	v_max_f32_e32 v83, 0, v83
	v_max_f32_e32 v84, 0, v84
	v_max_f32_e32 v85, 0, v85
	v_max_f32_e32 v86, 0, v86
	v_max_f32_e32 v87, 0, v87
	v_mul_f32_e32 v92, v92, v92
	v_mul_f32_e32 v88, v88, v88
	v_mul_f32_e32 v93, v93, v93
	v_mul_f32_e32 v89, v89, v89
	v_mul_f32_e32 v94, v94, v94
	v_mul_f32_e32 v90, v90, v90
	v_mul_f32_e32 v95, v95, v95
	v_mul_f32_e32 v91, v91, v91
	v_mul_f32_e32 v102, v80, v80
	v_mul_f32_e32 v103, v81, v81
	v_mul_f32_e32 v104, v82, v82
	v_mul_f32_e32 v105, v83, v83
	v_cvt_pk_bf16_f32 v80, v92, v93
	v_cvt_pk_bf16_f32 v81, v94, v95
	v_cvt_pk_bf16_f32 v82, v88, v89
	v_cvt_pk_bf16_f32 v83, v90, v91
	v_lshl_add_u64 v[100:101], v[96:97], 2, s[16:17]
	v_mul_f32_e32 v84, v84, v84
	v_mul_f32_e32 v85, v85, v85
	v_mul_f32_e32 v86, v86, v86
	v_mul_f32_e32 v87, v87, v87
	global_store_dwordx4 v[98:99], v[80:83], off
	s_nop 1
	v_cvt_pk_bf16_f32 v80, v84, v85
	v_cvt_pk_bf16_f32 v81, v86, v87
	v_cvt_pk_bf16_f32 v82, v102, v103
	v_cvt_pk_bf16_f32 v83, v104, v105
	global_store_dwordx4 v[98:99], v[80:83], off offset:256
	s_nop 0
	s_nop 0
	v_fmamk_f32 v80, v228, 0x3a800000, v158
	v_mul_f32_e32 v81, 0x4b800000, v80
	v_cmp_gt_f32_e32 vcc, s62, v80
	s_nop 1
	v_cndmask_b32_e32 v80, v80, v81, vcc
	v_rsq_f32_e32 v82, v80
	v_lshlrev_b64 v[80:81], 13, v[96:97]
	v_lshl_add_u64 v[80:81], s[14:15], 0, v[80:81]
	v_lshl_add_u64 v[80:81], v[80:81], 0, v[150:151]
	v_mul_f32_e32 v83, 0x45800000, v82
	v_cndmask_b32_e32 v82, v82, v83, vcc
	v_mul_f32_e32 v78, v78, v82
	v_mul_f32_e32 v79, v79, v82
	v_mul_f32_e32 v76, v76, v82
	v_mul_f32_e32 v77, v77, v82
	v_mul_f32_e32 v74, v74, v82
	v_mul_f32_e32 v75, v75, v82
	v_mul_f32_e32 v72, v72, v82
	v_mul_f32_e32 v73, v73, v82
	v_mul_f32_e32 v66, v66, v82
	v_mul_f32_e32 v67, v67, v82
	v_mul_f32_e32 v64, v64, v82
	v_mul_f32_e32 v65, v65, v82
	v_mul_f32_e32 v70, v70, v82
	v_mul_f32_e32 v71, v71, v82
	v_mul_f32_e32 v68, v68, v82
	v_mul_f32_e32 v69, v69, v82
	v_max_f32_e32 v76, 0, v76
	v_max_f32_e32 v72, 0, v72
	v_max_f32_e32 v77, 0, v77
	v_max_f32_e32 v73, 0, v73
	v_max_f32_e32 v78, 0, v78
	v_max_f32_e32 v74, 0, v74
	v_max_f32_e32 v79, 0, v79
	v_max_f32_e32 v75, 0, v75
	v_max_f32_e32 v64, 0, v64
	v_max_f32_e32 v65, 0, v65
	v_max_f32_e32 v66, 0, v66
	v_max_f32_e32 v67, 0, v67
	v_max_f32_e32 v68, 0, v68
	v_max_f32_e32 v69, 0, v69
	v_max_f32_e32 v70, 0, v70
	v_max_f32_e32 v71, 0, v71
	v_mul_f32_e32 v76, v76, v76
	v_mul_f32_e32 v72, v72, v72
	v_mul_f32_e32 v77, v77, v77
	v_mul_f32_e32 v73, v73, v73
	v_mul_f32_e32 v78, v78, v78
	v_mul_f32_e32 v74, v74, v74
	v_mul_f32_e32 v79, v79, v79
	v_mul_f32_e32 v75, v75, v75
	v_mul_f32_e32 v82, v64, v64
	v_mul_f32_e32 v83, v65, v65
	v_mul_f32_e32 v84, v66, v66
	v_mul_f32_e32 v85, v67, v67
	v_cvt_pk_bf16_f32 v64, v76, v77
	v_cvt_pk_bf16_f32 v65, v78, v79
	v_cvt_pk_bf16_f32 v66, v72, v73
	v_cvt_pk_bf16_f32 v67, v74, v75
	v_mul_f32_e32 v68, v68, v68
	v_mul_f32_e32 v69, v69, v69
	v_mul_f32_e32 v70, v70, v70
	v_mul_f32_e32 v71, v71, v71
	global_store_dwordx4 v[80:81], v[64:67], off
	s_nop 1
	v_cvt_pk_bf16_f32 v64, v68, v69
	v_cvt_pk_bf16_f32 v65, v70, v71
	v_cvt_pk_bf16_f32 v66, v82, v83
	v_cvt_pk_bf16_f32 v67, v84, v85
	global_store_dwordx4 v[80:81], v[64:67], off offset:256
	s_nop 0
	s_nop 0
	v_lshl_add_u64 v[64:65], v[146:147], 0, s[20:21]
	s_nop 0
	v_fmamk_f32 v66, v229, 0x3a800000, v158
	v_mul_f32_e32 v67, 0x4b800000, v66
	v_cmp_gt_f32_e32 vcc, s62, v66
	s_nop 1
	v_cndmask_b32_e32 v66, v66, v67, vcc
	v_rsq_f32_e32 v68, v66
	v_add_co_u32_e64 v66, s[6:7], s63, v146
	v_mul_f32_e32 v69, 0x45800000, v68
	v_cndmask_b32_e32 v68, v68, v69, vcc
	v_mul_f32_e32 v62, v62, v68
	v_mul_f32_e32 v63, v63, v68
	v_mul_f32_e32 v60, v60, v68
	v_mul_f32_e32 v61, v61, v68
	v_mul_f32_e32 v58, v58, v68
	v_mul_f32_e32 v59, v59, v68
	v_mul_f32_e32 v56, v56, v68
	v_mul_f32_e32 v57, v57, v68
	v_mul_f32_e32 v50, v50, v68
	v_mul_f32_e32 v51, v51, v68
	v_mul_f32_e32 v48, v48, v68
	v_mul_f32_e32 v49, v49, v68
	v_mul_f32_e32 v54, v54, v68
	v_mul_f32_e32 v55, v55, v68
	v_mul_f32_e32 v52, v52, v68
	v_mul_f32_e32 v53, v53, v68
	v_max_f32_e32 v60, 0, v60
	v_max_f32_e32 v56, 0, v56
	v_max_f32_e32 v61, 0, v61
	v_max_f32_e32 v57, 0, v57
	v_max_f32_e32 v62, 0, v62
	v_max_f32_e32 v58, 0, v58
	v_max_f32_e32 v63, 0, v63
	v_max_f32_e32 v59, 0, v59
	v_max_f32_e32 v48, 0, v48
	v_max_f32_e32 v49, 0, v49
	v_max_f32_e32 v50, 0, v50
	v_max_f32_e32 v51, 0, v51
	v_addc_co_u32_e64 v67, s[6:7], 0, v147, s[6:7]
	v_max_f32_e32 v52, 0, v52
	v_max_f32_e32 v53, 0, v53
	v_max_f32_e32 v54, 0, v54
	v_max_f32_e32 v55, 0, v55
	v_mul_f32_e32 v60, v60, v60
; __device__ __forceinline__ unsigned cvt_pk_bf16(float lo, float hi) { unsigned r; asm volatile("v_cvt_pk_bf16_f32 %0, %1, %2" : "=v"(r) : "v"(lo), "v"(hi)); return r; }
;     DI void operator()(const f32x4 (&acc)[2][2][4][2], const Unit& u, int wr, int wc, int fr, int fq) const {
;     ...
;             for (int m = 0; m < 4; ++m) { const int row = row0 + ai * 128 + m * 16; const float s = rsqrtf(ssum2[row] * (1.f / 1024.f) + EPS);
;                 bf16_t* rowp = U + (size_t)row * 4096 + col0;
; #pragma unroll
;                 for (int bj = 0; bj < 2; ++bj) { f32x4 v0 = acc[ai][bj][m][0] * s, v1 = acc[ai][bj][m][1] * s;
; #pragma unroll
;                     for (int j = 0; j < 4; ++j) { const float a = fmaxf(v0[j], 0.f), b = fmaxf(v1[j], 0.f); v0[j] = a * a; v1[j] = b * b; }
;                     u32x4 w; w.x = cvt_pk_bf16(v0[0], v0[1]); w.y = cvt_pk_bf16(v0[2], v0[3]); w.z = cvt_pk_bf16(v1[0], v1[1]); w.w = cvt_pk_bf16(v1[2], v1[3]);
;                     __builtin_nontemporal_store(w, (u32x4*)(rowp + bj * 128)); } }
	v_mul_f32_e32 v56, v56, v56
	v_mul_f32_e32 v61, v61, v61
	v_mul_f32_e32 v57, v57, v57
	v_mul_f32_e32 v62, v62, v62
	v_mul_f32_e32 v58, v58, v58
	v_mul_f32_e32 v63, v63, v63
	v_mul_f32_e32 v59, v59, v59
	v_mul_f32_e32 v68, v48, v48
	v_mul_f32_e32 v69, v49, v49
	v_mul_f32_e32 v70, v50, v50
	v_mul_f32_e32 v71, v51, v51
	v_cvt_pk_bf16_f32 v48, v60, v61
	v_cvt_pk_bf16_f32 v49, v62, v63
	v_cvt_pk_bf16_f32 v50, v56, v57
	v_cvt_pk_bf16_f32 v51, v58, v59
	v_mul_f32_e32 v52, v52, v52
	v_mul_f32_e32 v53, v53, v53
	v_mul_f32_e32 v54, v54, v54
	v_mul_f32_e32 v55, v55, v55
	global_store_dwordx4 v[66:67], v[48:51], off
	s_nop 1
	v_cvt_pk_bf16_f32 v48, v52, v53
	v_cvt_pk_bf16_f32 v49, v54, v55
	v_cvt_pk_bf16_f32 v50, v68, v69
	v_cvt_pk_bf16_f32 v51, v70, v71
	global_store_dwordx4 v[64:65], v[48:51], off offset:256
	s_nop 0
	s_nop 0
	v_lshl_add_u64 v[48:49], v[146:147], 0, s[22:23]
	s_nop 0
	v_fmamk_f32 v50, v230, 0x3a800000, v158
	v_mul_f32_e32 v51, 0x4b800000, v50
	v_cmp_gt_f32_e32 vcc, s62, v50
	s_nop 1
	v_cndmask_b32_e32 v50, v50, v51, vcc
	v_rsq_f32_e32 v52, v50
	v_add_co_u32_e64 v50, s[6:7], s64, v146
	v_mul_f32_e32 v53, 0x45800000, v52
	v_cndmask_b32_e32 v52, v52, v53, vcc
	v_mul_f32_e32 v46, v46, v52
	v_mul_f32_e32 v47, v47, v52
	v_mul_f32_e32 v44, v44, v52
	v_mul_f32_e32 v45, v45, v52
	v_mul_f32_e32 v42, v42, v52
	v_mul_f32_e32 v43, v43, v52
	v_mul_f32_e32 v40, v40, v52
	v_mul_f32_e32 v41, v41, v52
	v_mul_f32_e32 v34, v34, v52
	v_mul_f32_e32 v35, v35, v52
	v_mul_f32_e32 v32, v32, v52
	v_mul_f32_e32 v33, v33, v52
	v_mul_f32_e32 v38, v38, v52
	v_mul_f32_e32 v39, v39, v52
	v_mul_f32_e32 v36, v36, v52
	v_mul_f32_e32 v37, v37, v52
	v_max_f32_e32 v44, 0, v44
	v_max_f32_e32 v40, 0, v40
	v_max_f32_e32 v45, 0, v45
	v_max_f32_e32 v41, 0, v41
	v_max_f32_e32 v46, 0, v46
	v_max_f32_e32 v42, 0, v42
	v_max_f32_e32 v47, 0, v47
	v_max_f32_e32 v43, 0, v43
	v_max_f32_e32 v32, 0, v32
	v_max_f32_e32 v33, 0, v33
	v_max_f32_e32 v34, 0, v34
	v_max_f32_e32 v35, 0, v35
	v_addc_co_u32_e64 v51, s[6:7], 0, v147, s[6:7]
	v_max_f32_e32 v36, 0, v36
	v_max_f32_e32 v37, 0, v37
	v_max_f32_e32 v38, 0, v38
	v_max_f32_e32 v39, 0, v39
	v_mul_f32_e32 v44, v44, v44
	v_mul_f32_e32 v40, v40, v40
	v_mul_f32_e32 v45, v45, v45
	v_mul_f32_e32 v41, v41, v41
	v_mul_f32_e32 v46, v46, v46
	v_mul_f32_e32 v42, v42, v42
	v_mul_f32_e32 v47, v47, v47
	v_mul_f32_e32 v43, v43, v43
	v_mul_f32_e32 v52, v32, v32
	v_mul_f32_e32 v53, v33, v33
	v_mul_f32_e32 v54, v34, v34
	v_mul_f32_e32 v55, v35, v35
	v_cvt_pk_bf16_f32 v32, v44, v45
	v_cvt_pk_bf16_f32 v33, v46, v47
	v_cvt_pk_bf16_f32 v34, v40, v41
	v_cvt_pk_bf16_f32 v35, v42, v43
	v_mul_f32_e32 v36, v36, v36
	v_mul_f32_e32 v37, v37, v37
	v_mul_f32_e32 v38, v38, v38
	v_mul_f32_e32 v39, v39, v39
	global_store_dwordx4 v[50:51], v[32:35], off
	s_nop 1
	v_cvt_pk_bf16_f32 v32, v36, v37
	v_cvt_pk_bf16_f32 v33, v38, v39
	v_cvt_pk_bf16_f32 v34, v52, v53
	v_cvt_pk_bf16_f32 v35, v54, v55
	global_store_dwordx4 v[48:49], v[32:35], off offset:256
	s_nop 0
	s_nop 0
	v_lshl_add_u64 v[32:33], v[146:147], 0, s[24:25]
	s_nop 0
	v_fmamk_f32 v34, v231, 0x3a800000, v158
	v_mul_f32_e32 v35, 0x4b800000, v34
	v_cmp_gt_f32_e32 vcc, s62, v34
	s_nop 1
	v_cndmask_b32_e32 v34, v34, v35, vcc
	v_rsq_f32_e32 v36, v34
	v_add_co_u32_e64 v34, s[6:7], s65, v146
	v_mul_f32_e32 v37, 0x45800000, v36
	v_cndmask_b32_e32 v36, v36, v37, vcc
	v_mul_f32_e32 v30, v30, v36
	v_mul_f32_e32 v31, v31, v36
	v_mul_f32_e32 v28, v28, v36
	v_mul_f32_e32 v29, v29, v36
	v_mul_f32_e32 v26, v26, v36
	v_mul_f32_e32 v27, v27, v36
	v_mul_f32_e32 v24, v24, v36
	v_mul_f32_e32 v25, v25, v36
	v_mul_f32_e32 v18, v18, v36
	v_mul_f32_e32 v19, v19, v36
	v_mul_f32_e32 v16, v16, v36
	v_mul_f32_e32 v17, v17, v36
; __device__ __forceinline__ unsigned cvt_pk_bf16(float lo, float hi) { unsigned r; asm volatile("v_cvt_pk_bf16_f32 %0, %1, %2" : "=v"(r) : "v"(lo), "v"(hi)); return r; }
;     DI void operator()(const f32x4 (&acc)[2][2][4][2], const Unit& u, int wr, int wc, int fr, int fq) const {
;     ...
;             for (int m = 0; m < 4; ++m) { const int row = row0 + ai * 128 + m * 16; const float s = rsqrtf(ssum2[row] * (1.f / 1024.f) + EPS);
;                 bf16_t* rowp = U + (size_t)row * 4096 + col0;
; #pragma unroll
;                 for (int bj = 0; bj < 2; ++bj) { f32x4 v0 = acc[ai][bj][m][0] * s, v1 = acc[ai][bj][m][1] * s;
; #pragma unroll
;                     for (int j = 0; j < 4; ++j) { const float a = fmaxf(v0[j], 0.f), b = fmaxf(v1[j], 0.f); v0[j] = a * a; v1[j] = b * b; }
;                     u32x4 w; w.x = cvt_pk_bf16(v0[0], v0[1]); w.y = cvt_pk_bf16(v0[2], v0[3]); w.z = cvt_pk_bf16(v1[0], v1[1]); w.w = cvt_pk_bf16(v1[2], v1[3]);
;                     __builtin_nontemporal_store(w, (u32x4*)(rowp + bj * 128)); } }
	v_mul_f32_e32 v22, v22, v36
	v_mul_f32_e32 v23, v23, v36
	v_mul_f32_e32 v20, v20, v36
	v_mul_f32_e32 v21, v21, v36
	v_max_f32_e32 v28, 0, v28
	v_max_f32_e32 v24, 0, v24
	v_max_f32_e32 v29, 0, v29
	v_max_f32_e32 v25, 0, v25
	v_max_f32_e32 v30, 0, v30
	v_max_f32_e32 v26, 0, v26
	v_max_f32_e32 v31, 0, v31
	v_max_f32_e32 v27, 0, v27
	v_max_f32_e32 v16, 0, v16
	v_max_f32_e32 v17, 0, v17
	v_max_f32_e32 v18, 0, v18
	v_max_f32_e32 v19, 0, v19
	v_addc_co_u32_e64 v35, s[6:7], 0, v147, s[6:7]
	v_max_f32_e32 v20, 0, v20
	v_max_f32_e32 v21, 0, v21
	v_max_f32_e32 v22, 0, v22
	v_max_f32_e32 v23, 0, v23
	v_mul_f32_e32 v28, v28, v28
	v_mul_f32_e32 v24, v24, v24
	v_mul_f32_e32 v29, v29, v29
	v_mul_f32_e32 v25, v25, v25
	v_mul_f32_e32 v30, v30, v30
	v_mul_f32_e32 v26, v26, v26
	v_mul_f32_e32 v31, v31, v31
	v_mul_f32_e32 v27, v27, v27
	v_mul_f32_e32 v36, v16, v16
	v_mul_f32_e32 v37, v17, v17
	v_mul_f32_e32 v38, v18, v18
	v_mul_f32_e32 v39, v19, v19
	v_cvt_pk_bf16_f32 v16, v28, v29
	v_cvt_pk_bf16_f32 v17, v30, v31
	v_cvt_pk_bf16_f32 v18, v24, v25
	v_cvt_pk_bf16_f32 v19, v26, v27
	v_mul_f32_e32 v20, v20, v20
	v_mul_f32_e32 v21, v21, v21
	v_mul_f32_e32 v22, v22, v22
	v_mul_f32_e32 v23, v23, v23
	global_store_dwordx4 v[34:35], v[16:19], off
	s_andn2_b64 vcc, exec, s[4:5]
	s_nop 0
	v_cvt_pk_bf16_f32 v16, v20, v21
	v_cvt_pk_bf16_f32 v17, v22, v23
	v_cvt_pk_bf16_f32 v18, v36, v37
	v_cvt_pk_bf16_f32 v19, v38, v39
	global_store_dwordx4 v[32:33], v[16:19], off offset:256
	s_nop 0
	s_nop 0
	v_lshl_add_u64 v[16:17], v[146:147], 0, s[26:27]
	s_nop 0
	v_fmamk_f32 v18, v232, 0x3a800000, v158
	v_mul_f32_e32 v19, 0x4b800000, v18
	v_cmp_gt_f32_e64 s[4:5], s62, v18
	s_nop 1
	v_cndmask_b32_e64 v18, v18, v19, s[4:5]
	v_rsq_f32_e32 v20, v18
	v_add_co_u32_e64 v18, s[6:7], s66, v146
	v_mul_f32_e32 v21, 0x45800000, v20
	v_cndmask_b32_e64 v20, v20, v21, s[4:5]
	v_mul_f32_e32 v14, v14, v20
	v_mul_f32_e32 v15, v15, v20
	v_mul_f32_e32 v12, v12, v20
	v_mul_f32_e32 v13, v13, v20
	v_mul_f32_e32 v10, v10, v20
	v_mul_f32_e32 v11, v11, v20
	v_mul_f32_e32 v8, v8, v20
	v_mul_f32_e32 v9, v9, v20
	v_mul_f32_e32 v2, v2, v20
	v_mul_f32_e32 v3, v3, v20
	v_mul_f32_e32 v0, v0, v20
	v_mul_f32_e32 v1, v1, v20
	v_mul_f32_e32 v6, v6, v20
	v_mul_f32_e32 v7, v7, v20
	v_mul_f32_e32 v4, v4, v20
	v_mul_f32_e32 v5, v5, v20
	v_max_f32_e32 v12, 0, v12
	v_max_f32_e32 v8, 0, v8
	v_max_f32_e32 v13, 0, v13
	v_max_f32_e32 v9, 0, v9
	v_max_f32_e32 v14, 0, v14
	v_max_f32_e32 v10, 0, v10
	v_max_f32_e32 v15, 0, v15
	v_max_f32_e32 v11, 0, v11
	v_max_f32_e32 v0, 0, v0
	v_max_f32_e32 v1, 0, v1
	v_max_f32_e32 v2, 0, v2
	v_max_f32_e32 v3, 0, v3
	v_addc_co_u32_e64 v19, s[6:7], 0, v147, s[6:7]
	v_max_f32_e32 v4, 0, v4
	v_max_f32_e32 v5, 0, v5
	v_max_f32_e32 v6, 0, v6
	v_max_f32_e32 v7, 0, v7
	v_mul_f32_e32 v12, v12, v12
	v_mul_f32_e32 v8, v8, v8
	v_mul_f32_e32 v13, v13, v13
	v_mul_f32_e32 v9, v9, v9
	v_mul_f32_e32 v14, v14, v14
	v_mul_f32_e32 v10, v10, v10
	v_mul_f32_e32 v15, v15, v15
	v_mul_f32_e32 v11, v11, v11
	v_mul_f32_e32 v20, v0, v0
	v_mul_f32_e32 v21, v1, v1
	v_mul_f32_e32 v22, v2, v2
	v_mul_f32_e32 v23, v3, v3
	v_cvt_pk_bf16_f32 v0, v12, v13
	v_cvt_pk_bf16_f32 v1, v14, v15
	v_cvt_pk_bf16_f32 v2, v8, v9
	v_cvt_pk_bf16_f32 v3, v10, v11
	s_mov_b64 s[4:5], -1
	v_mul_f32_e32 v4, v4, v4
	v_mul_f32_e32 v5, v5, v5
	v_mul_f32_e32 v6, v6, v6
	v_mul_f32_e32 v7, v7, v7
	global_store_dwordx4 v[18:19], v[0:3], off
	s_nop 1
	v_cvt_pk_bf16_f32 v0, v4, v5
	v_cvt_pk_bf16_f32 v1, v6, v7
	v_cvt_pk_bf16_f32 v2, v20, v21
	v_cvt_pk_bf16_f32 v3, v22, v23
	global_store_dwordx4 v[16:17], v[0:3], off offset:256
	s_cbranch_vccnz .LBB0_2059
	s_andn2_b64 vcc, exec, s[8:9]
	s_cbranch_vccnz .LBB0_2058
	s_barrier
	s_branch .LBB0_2058
